# c13_o28 + s_setprio 2 for waves 0-3 during the GDN diagonal-block inverse (latency-bound chain), back to 0 after
# baseline (speedup 1.0000x reference)
.Lgt_inv:
	s_setprio 2
	v_cmp_gt_u32_e32 vcc, 16, v3
	s_and_saveexec_b64 s[10:11], vcc
	s_cbranch_execz .Lgt_invend
	v_mov_b32_e32 v119, s97
	ds_read_b128 v[120:123], v119 offset:0
	ds_read_b128 v[124:127], v119 offset:16
	ds_read_b128 v[128:131], v119 offset:32
	ds_read_b128 v[132:135], v119 offset:48
	ds_read_b128 v[142:145], v119 offset:80
	ds_read_b128 v[146:149], v119 offset:96
	ds_read_b128 v[150:153], v119 offset:112
	ds_read_b128 v[154:157], v119 offset:128
	ds_read_b128 v[158:161], v119 offset:160
	ds_read_b128 v[236:239], v119 offset:176
	ds_read_b128 v[240:243], v119 offset:192
	ds_read_b128 v[244:247], v119 offset:208
	ds_read_b128 v[248:251], v119 offset:256
	ds_read_b128 v[252:255], v119 offset:272
	ds_read_b128 v[108:111], v119 offset:288
	ds_read_b128 v[112:115], v119 offset:336
	s_mov_b64 s[12:13], 0x1
	v_cndmask_b32_e64 v210, 0, 1.0, s[12:13]
	s_mov_b64 s[48:49], 0x2
	v_cndmask_b32_e64 v211, 0, 1.0, s[48:49]
	s_mov_b64 s[50:51], 0x4
	v_cndmask_b32_e64 v212, 0, 1.0, s[50:51]
	s_mov_b64 s[12:13], 0x8
	v_cndmask_b32_e64 v213, 0, 1.0, s[12:13]
	s_mov_b64 s[48:49], 0x10
	v_cndmask_b32_e64 v214, 0, 1.0, s[48:49]
	s_mov_b64 s[50:51], 0x20
	v_cndmask_b32_e64 v215, 0, 1.0, s[50:51]
	s_mov_b64 s[12:13], 0x40
	v_cndmask_b32_e64 v216, 0, 1.0, s[12:13]
	s_mov_b64 s[48:49], 0x80
	v_cndmask_b32_e64 v217, 0, 1.0, s[48:49]
	s_mov_b64 s[50:51], 0x100
	v_cndmask_b32_e64 v218, 0, 1.0, s[50:51]
	s_mov_b64 s[12:13], 0x200
	v_cndmask_b32_e64 v219, 0, 1.0, s[12:13]
	s_mov_b64 s[48:49], 0x400
	v_cndmask_b32_e64 v187, 0, 1.0, s[48:49]
	s_mov_b64 s[50:51], 0x800
	v_cndmask_b32_e64 v164, 0, 1.0, s[50:51]
	s_mov_b64 s[12:13], 0x1000
	v_cndmask_b32_e64 v165, 0, 1.0, s[12:13]
	s_mov_b64 s[48:49], 0x2000
	v_cndmask_b32_e64 v166, 0, 1.0, s[48:49]
	s_mov_b64 s[50:51], 0x4000
	v_cndmask_b32_e64 v167, 0, 1.0, s[50:51]
	s_mov_b64 s[12:13], 0x8000
	v_cndmask_b32_e64 v168, 0, 1.0, s[12:13]
	s_waitcnt lgkmcnt(12)
	v_fma_f32 v211, -v121, v210, v211
	v_fma_f32 v212, -v122, v210, v212
	v_fma_f32 v213, -v123, v210, v213
	v_fma_f32 v214, -v124, v210, v214
	v_fma_f32 v215, -v125, v210, v215
	v_fma_f32 v216, -v126, v210, v216
	v_fma_f32 v217, -v127, v210, v217
	v_fma_f32 v218, -v128, v210, v218
	v_fma_f32 v219, -v129, v210, v219
	v_fma_f32 v187, -v130, v210, v187
	v_fma_f32 v164, -v131, v210, v164
	v_fma_f32 v165, -v132, v210, v165
	v_fma_f32 v166, -v133, v210, v166
	v_fma_f32 v167, -v134, v210, v167
	v_fma_f32 v168, -v135, v210, v168
	ds_read_b128 v[120:123], v119 offset:352
	ds_read_b128 v[124:127], v119 offset:368
	ds_read_b128 v[128:131], v119 offset:416
	ds_read_b128 v[132:135], v119 offset:432
	s_waitcnt lgkmcnt(12)
	v_fma_f32 v212, -v144, v211, v212
	v_fma_f32 v213, -v145, v211, v213
	v_fma_f32 v214, -v146, v211, v214
	v_fma_f32 v215, -v147, v211, v215
	v_fma_f32 v216, -v148, v211, v216
	v_fma_f32 v217, -v149, v211, v217
	v_fma_f32 v218, -v150, v211, v218
	v_fma_f32 v219, -v151, v211, v219
	v_fma_f32 v187, -v152, v211, v187
	v_fma_f32 v164, -v153, v211, v164
	v_fma_f32 v165, -v154, v211, v165
	v_fma_f32 v166, -v155, v211, v166
	v_fma_f32 v167, -v156, v211, v167
	v_fma_f32 v168, -v157, v211, v168
	ds_read_b128 v[142:145], v119 offset:448
	ds_read_b128 v[146:149], v119 offset:496
	ds_read_b128 v[150:153], v119 offset:512
	ds_read_b128 v[154:157], v119 offset:528
	s_waitcnt lgkmcnt(12)
	v_fma_f32 v213, -v161, v212, v213
	v_fma_f32 v214, -v236, v212, v214
	v_fma_f32 v215, -v237, v212, v215
	v_fma_f32 v216, -v238, v212, v216
	v_fma_f32 v217, -v239, v212, v217
	v_fma_f32 v218, -v240, v212, v218
	v_fma_f32 v219, -v241, v212, v219
	v_fma_f32 v187, -v242, v212, v187
	v_fma_f32 v164, -v243, v212, v164
	v_fma_f32 v165, -v244, v212, v165
	v_fma_f32 v166, -v245, v212, v166
	v_fma_f32 v167, -v246, v212, v167
	v_fma_f32 v168, -v247, v212, v168
	ds_read_b128 v[158:161], v119 offset:592
	ds_read_b128 v[236:239], v119 offset:608
	ds_read_b128 v[240:243], v119 offset:672
	ds_read_b128 v[244:247], v119 offset:688
	s_waitcnt lgkmcnt(13)
	v_fma_f32 v214, -v248, v213, v214
	v_fma_f32 v215, -v249, v213, v215
	v_fma_f32 v216, -v250, v213, v216
	v_fma_f32 v217, -v251, v213, v217
	v_fma_f32 v218, -v252, v213, v218
	v_fma_f32 v219, -v253, v213, v219
	v_fma_f32 v187, -v254, v213, v187
	v_fma_f32 v164, -v255, v213, v164
	v_fma_f32 v165, -v108, v213, v165
	v_fma_f32 v166, -v109, v213, v166
	v_fma_f32 v167, -v110, v213, v167
	v_fma_f32 v168, -v111, v213, v168
	ds_read_b128 v[248:251], v119 offset:752
	ds_read_b128 v[252:255], v119 offset:768
	ds_read_b128 v[108:111], v119 offset:832
	s_waitcnt lgkmcnt(13)
	v_fma_f32 v215, -v113, v214, v215
	v_fma_f32 v216, -v114, v214, v216
	v_fma_f32 v217, -v115, v214, v217
	v_fma_f32 v218, -v120, v214, v218
	v_fma_f32 v219, -v121, v214, v219
	v_fma_f32 v187, -v122, v214, v187
	v_fma_f32 v164, -v123, v214, v164
	v_fma_f32 v165, -v124, v214, v165
	v_fma_f32 v166, -v125, v214, v166
	v_fma_f32 v167, -v126, v214, v167
	v_fma_f32 v168, -v127, v214, v168
	ds_read_b128 v[112:115], v119 offset:848
	ds_read_b128 v[120:123], v119 offset:928
	ds_read_b128 v[124:127], v119 offset:1008
	s_waitcnt lgkmcnt(13)
	v_fma_f32 v216, -v130, v215, v216
	v_fma_f32 v217, -v131, v215, v217
	v_fma_f32 v218, -v132, v215, v218
	v_fma_f32 v219, -v133, v215, v219
	v_fma_f32 v187, -v134, v215, v187
	v_fma_f32 v164, -v135, v215, v164
	v_fma_f32 v165, -v142, v215, v165
	v_fma_f32 v166, -v143, v215, v166
	v_fma_f32 v167, -v144, v215, v167
	v_fma_f32 v168, -v145, v215, v168
	ds_read_b128 v[128:131], v119 offset:1088
	ds_read_b128 v[132:135], v119 offset:1168
	s_waitcnt lgkmcnt(12)
	v_fma_f32 v217, -v149, v216, v217
	v_fma_f32 v218, -v150, v216, v218
	v_fma_f32 v219, -v151, v216, v219
	v_fma_f32 v187, -v152, v216, v187
	v_fma_f32 v164, -v153, v216, v164
	v_fma_f32 v165, -v154, v216, v165
	v_fma_f32 v166, -v155, v216, v166
	v_fma_f32 v167, -v156, v216, v167
	v_fma_f32 v168, -v157, v216, v168
	s_waitcnt lgkmcnt(10)
	v_fma_f32 v218, -v158, v217, v218
	v_fma_f32 v219, -v159, v217, v219
	v_fma_f32 v187, -v160, v217, v187
	v_fma_f32 v164, -v161, v217, v164
	v_fma_f32 v165, -v236, v217, v165
	v_fma_f32 v166, -v237, v217, v166
	v_fma_f32 v167, -v238, v217, v167
	v_fma_f32 v168, -v239, v217, v168
	s_waitcnt lgkmcnt(8)
	v_fma_f32 v219, -v241, v218, v219
	v_fma_f32 v187, -v242, v218, v187
	v_fma_f32 v164, -v243, v218, v164
	v_fma_f32 v165, -v244, v218, v165
	v_fma_f32 v166, -v245, v218, v166
	v_fma_f32 v167, -v246, v218, v167
	v_fma_f32 v168, -v247, v218, v168
	s_waitcnt lgkmcnt(6)
	v_fma_f32 v187, -v250, v219, v187
	v_fma_f32 v164, -v251, v219, v164
	v_fma_f32 v165, -v252, v219, v165
	v_fma_f32 v166, -v253, v219, v166
	v_fma_f32 v167, -v254, v219, v167
	v_fma_f32 v168, -v255, v219, v168
	s_waitcnt lgkmcnt(4)
	v_fma_f32 v164, -v111, v187, v164
	v_fma_f32 v165, -v112, v187, v165
	v_fma_f32 v166, -v113, v187, v166
	v_fma_f32 v167, -v114, v187, v167
	v_fma_f32 v168, -v115, v187, v168
	s_waitcnt lgkmcnt(3)
	v_fma_f32 v165, -v120, v164, v165
	v_fma_f32 v166, -v121, v164, v166
	v_fma_f32 v167, -v122, v164, v167
	v_fma_f32 v168, -v123, v164, v168
	s_waitcnt lgkmcnt(2)
	v_fma_f32 v166, -v125, v165, v166
	v_fma_f32 v167, -v126, v165, v167
	v_fma_f32 v168, -v127, v165, v168
	s_waitcnt lgkmcnt(1)
	v_fma_f32 v167, -v130, v166, v167
	v_fma_f32 v168, -v131, v166, v168
	s_waitcnt lgkmcnt(0)
	v_fma_f32 v168, -v135, v167, v168
	v_lshl_add_u32 v169, v3, 1, s88
	v_cvt_pk_bf16_f32 v170, v210, s0
	ds_write_b16 v169, v170 offset:0
	v_cvt_pk_bf16_f32 v171, v211, s0
	ds_write_b16 v169, v171 offset:40
	v_cvt_pk_bf16_f32 v170, v212, s0
	ds_write_b16 v169, v170 offset:80
	v_cvt_pk_bf16_f32 v171, v213, s0
	ds_write_b16 v169, v171 offset:120
	v_cvt_pk_bf16_f32 v170, v214, s0
	ds_write_b16 v169, v170 offset:160
	v_cvt_pk_bf16_f32 v171, v215, s0
	ds_write_b16 v169, v171 offset:200
	v_cvt_pk_bf16_f32 v170, v216, s0
	ds_write_b16 v169, v170 offset:240
	v_cvt_pk_bf16_f32 v171, v217, s0
	ds_write_b16 v169, v171 offset:280
	v_cvt_pk_bf16_f32 v170, v218, s0
	ds_write_b16 v169, v170 offset:320
	v_cvt_pk_bf16_f32 v171, v219, s0
	ds_write_b16 v169, v171 offset:360
	v_cvt_pk_bf16_f32 v170, v187, s0
	ds_write_b16 v169, v170 offset:400
	v_cvt_pk_bf16_f32 v171, v164, s0
	ds_write_b16 v169, v171 offset:440
	v_cvt_pk_bf16_f32 v170, v165, s0
	ds_write_b16 v169, v170 offset:480
	v_cvt_pk_bf16_f32 v171, v166, s0
	ds_write_b16 v169, v171 offset:520
	v_cvt_pk_bf16_f32 v170, v167, s0
	ds_write_b16 v169, v170 offset:560
	v_cvt_pk_bf16_f32 v171, v168, s0
	ds_write_b16 v169, v171 offset:600
.Lgt_invend:
	s_or_b64 exec, exec, s[10:11]
	s_setprio 0
	s_nop 0
	s_nop 0
	s_nop 0
	s_nop 0
	s_nop 0
	s_nop 0
	s_nop 0
	s_nop 0
	s_nop 0
	s_nop 0
	s_nop 0
	s_nop 0
	s_nop 0
	s_nop 0
